# M_OUT epilogue: hoist 16 serialized h loads (saddr form), counted vmcnt
# speedup vs baseline: 1.0297x; 1.0297x over previous
.LBB0_698:
	s_add_i32 s65, s4, 2
	s_add_u32 s18, s0, 0x80
	s_addc_u32 s5, s1, 0
	s_add_i32 s66, 0, 0x10000
	v_add_u32_e32 v146, s66, v149
	ds_read_b128 v[142:145], v146
	ds_read_b128 v[152:155], v146 offset:1024
	ds_read_b128 v[156:159], v146 offset:2048
	ds_read_b128 v[160:163], v146 offset:3072
	s_cmp_eq_u32 s34, s4
	s_cselect_b32 s4, s10, s18
	s_cselect_b32 s5, s11, s5
	s_cselect_b32 s19, s13, s49
	s_cselect_b32 s18, s12, s48
	v_lshl_add_u64 v[146:147], s[0:1], 0, v[138:139]
	s_add_i32 m0, s22, 0xc000
	ds_read_b128 v[164:167], v150
	ds_read_b128 v[168:171], v150 offset:1024
	ds_read_b128 v[172:175], v150 offset:2048
	ds_read_b128 v[176:179], v150 offset:3072
	ds_read_b128 v[180:183], v150 offset:4096
	ds_read_b128 v[204:207], v150 offset:5120
	ds_read_b128 v[208:211], v150 offset:6144
	ds_read_b128 v[212:215], v150 offset:7168
	global_load_lds_dwordx4 v[146:147], off
	v_lshl_add_u64 v[146:147], s[0:1], 0, v[140:141]
	s_add_i32 m0, s22, 0xe000
	s_nop 0
	global_load_lds_dwordx4 v[146:147], off
	s_waitcnt lgkmcnt(8)
	s_barrier
	s_waitcnt lgkmcnt(0)
	s_setprio 1
	s_waitcnt lgkmcnt(0)
	v_mfma_f32_16x16x32_bf16 v[126:129], v[142:145], v[164:167], v[126:129]
	v_mfma_f32_16x16x32_bf16 v[122:125], v[156:159], v[164:167], v[122:125]
	v_mfma_f32_16x16x32_bf16 v[110:113], v[142:145], v[172:175], v[110:113]
	v_mfma_f32_16x16x32_bf16 v[106:109], v[156:159], v[172:175], v[106:109]
	v_mfma_f32_16x16x32_bf16 v[94:97], v[142:145], v[180:183], v[94:97]
	v_mfma_f32_16x16x32_bf16 v[90:93], v[156:159], v[180:183], v[90:93]
	v_mfma_f32_16x16x32_bf16 v[78:81], v[142:145], v[208:211], v[78:81]
	v_mfma_f32_16x16x32_bf16 v[74:77], v[156:159], v[208:211], v[74:77]
	v_mfma_f32_16x16x32_bf16 v[126:129], v[152:155], v[168:171], v[126:129]
	v_mfma_f32_16x16x32_bf16 v[122:125], v[160:163], v[168:171], v[122:125]
	v_mfma_f32_16x16x32_bf16 v[110:113], v[152:155], v[176:179], v[110:113]
	v_mfma_f32_16x16x32_bf16 v[106:109], v[160:163], v[176:179], v[106:109]
	v_mfma_f32_16x16x32_bf16 v[94:97], v[152:155], v[204:207], v[94:97]
	v_mfma_f32_16x16x32_bf16 v[90:93], v[160:163], v[204:207], v[90:93]
	v_mfma_f32_16x16x32_bf16 v[78:81], v[152:155], v[212:215], v[78:81]
	v_mfma_f32_16x16x32_bf16 v[74:77], v[160:163], v[212:215], v[74:77]
	s_setprio 0
	s_barrier
	s_add_i32 s67, 0, 0x14000
	v_add_u32_e32 v146, s67, v149
	s_add_i32 s66, s66, s21
	ds_read_b128 v[216:219], v146
	ds_read_b128 v[220:223], v146 offset:1024
	ds_read_b128 v[224:227], v146 offset:2048
	ds_read_b128 v[228:231], v146 offset:3072
	v_lshl_add_u64 v[146:147], s[18:19], 0, v[132:133]
	s_mov_b32 m0, s66
	v_lshl_add_u64 v[184:185], s[18:19], 0, v[136:137]
	global_load_lds_dwordx4 v[146:147], off
	s_add_i32 m0, s66, 0x2000
	s_nop 0
	global_load_lds_dwordx4 v[184:185], off
	s_barrier
	s_waitcnt lgkmcnt(0)
	s_setprio 1
	s_waitcnt lgkmcnt(0)
	v_mfma_f32_16x16x32_bf16 v[118:121], v[216:219], v[164:167], v[118:121]
	v_mfma_f32_16x16x32_bf16 v[114:117], v[224:227], v[164:167], v[114:117]
	v_mfma_f32_16x16x32_bf16 v[102:105], v[216:219], v[172:175], v[102:105]
	v_mfma_f32_16x16x32_bf16 v[98:101], v[224:227], v[172:175], v[98:101]
	v_mfma_f32_16x16x32_bf16 v[86:89], v[216:219], v[180:183], v[86:89]
	v_mfma_f32_16x16x32_bf16 v[82:85], v[224:227], v[180:183], v[82:85]
	v_mfma_f32_16x16x32_bf16 v[70:73], v[216:219], v[208:211], v[70:73]
	v_mfma_f32_16x16x32_bf16 v[66:69], v[224:227], v[208:211], v[66:69]
	v_mfma_f32_16x16x32_bf16 v[118:121], v[220:223], v[168:171], v[118:121]
	v_mfma_f32_16x16x32_bf16 v[114:117], v[228:231], v[168:171], v[114:117]
	v_mfma_f32_16x16x32_bf16 v[102:105], v[220:223], v[176:179], v[102:105]
	v_mfma_f32_16x16x32_bf16 v[98:101], v[228:231], v[176:179], v[98:101]
	v_mfma_f32_16x16x32_bf16 v[86:89], v[220:223], v[204:207], v[86:89]
	v_mfma_f32_16x16x32_bf16 v[82:85], v[228:231], v[204:207], v[82:85]
	v_mfma_f32_16x16x32_bf16 v[70:73], v[220:223], v[212:215], v[70:73]
	v_mfma_f32_16x16x32_bf16 v[66:69], v[228:231], v[212:215], v[66:69]
	s_setprio 0
	s_mov_b32 m0, s22
	v_lshl_add_u64 v[232:233], s[4:5], 0, v[130:131]
	s_barrier
	ds_read_b128 v[164:167], v150 offset:16384
	ds_read_b128 v[168:171], v150 offset:17408
	ds_read_b128 v[172:175], v150 offset:18432
	ds_read_b128 v[176:179], v150 offset:19456
	ds_read_b128 v[180:183], v150 offset:20480
	ds_read_b128 v[204:207], v150 offset:21504
	ds_read_b128 v[208:211], v150 offset:22528
	ds_read_b128 v[212:215], v150 offset:23552
	global_load_lds_dwordx4 v[232:233], off
	v_lshl_add_u64 v[234:235], s[4:5], 0, v[134:135]
	s_mov_b32 m0, s23
	s_nop 0
	global_load_lds_dwordx4 v[234:235], off
	s_barrier
	s_waitcnt lgkmcnt(0)
	s_setprio 1
	s_waitcnt lgkmcnt(0)
	v_mfma_f32_16x16x32_bf16 v[62:65], v[142:145], v[164:167], v[62:65]
	v_mfma_f32_16x16x32_bf16 v[58:61], v[156:159], v[164:167], v[58:61]
	v_mfma_f32_16x16x32_bf16 v[46:49], v[142:145], v[172:175], v[46:49]
	v_mfma_f32_16x16x32_bf16 v[42:45], v[156:159], v[172:175], v[42:45]
	v_mfma_f32_16x16x32_bf16 v[30:33], v[142:145], v[180:183], v[30:33]
	v_mfma_f32_16x16x32_bf16 v[26:29], v[156:159], v[180:183], v[26:29]
	v_mfma_f32_16x16x32_bf16 v[14:17], v[142:145], v[208:211], v[14:17]
	v_mfma_f32_16x16x32_bf16 v[10:13], v[156:159], v[208:211], v[10:13]
	v_mfma_f32_16x16x32_bf16 v[62:65], v[152:155], v[168:171], v[62:65]
	v_mfma_f32_16x16x32_bf16 v[58:61], v[160:163], v[168:171], v[58:61]
	v_mfma_f32_16x16x32_bf16 v[46:49], v[152:155], v[176:179], v[46:49]
	v_mfma_f32_16x16x32_bf16 v[42:45], v[160:163], v[176:179], v[42:45]
	v_mfma_f32_16x16x32_bf16 v[30:33], v[152:155], v[204:207], v[30:33]
	v_mfma_f32_16x16x32_bf16 v[26:29], v[160:163], v[204:207], v[26:29]
	v_mfma_f32_16x16x32_bf16 v[14:17], v[152:155], v[212:215], v[14:17]
	v_mfma_f32_16x16x32_bf16 v[10:13], v[160:163], v[212:215], v[10:13]
	s_setprio 0
	s_barrier
	s_add_u32 s18, s18, s2
	s_addc_u32 s19, s19, 0
	s_add_i32 s66, s67, s21
	v_lshl_add_u64 v[236:237], s[18:19], 0, v[132:133]
	s_mov_b32 m0, s66
	v_lshl_add_u64 v[238:239], s[18:19], 0, v[136:137]
	global_load_lds_dwordx4 v[236:237], off
	s_add_i32 m0, s66, 0x2000
	s_nop 0
	global_load_lds_dwordx4 v[238:239], off
	s_waitcnt vmcnt(6)
	s_barrier
	s_setprio 1
	v_mfma_f32_16x16x32_bf16 v[54:57], v[216:219], v[164:167], v[54:57]
	v_mfma_f32_16x16x32_bf16 v[50:53], v[224:227], v[164:167], v[50:53]
	v_mfma_f32_16x16x32_bf16 v[38:41], v[216:219], v[172:175], v[38:41]
	v_mfma_f32_16x16x32_bf16 v[34:37], v[224:227], v[172:175], v[34:37]
	v_mfma_f32_16x16x32_bf16 v[22:25], v[216:219], v[180:183], v[22:25]
	v_mfma_f32_16x16x32_bf16 v[18:21], v[224:227], v[180:183], v[18:21]
	v_mfma_f32_16x16x32_bf16 v[6:9], v[216:219], v[208:211], v[6:9]
	v_mfma_f32_16x16x32_bf16 v[2:5], v[224:227], v[208:211], v[2:5]
	v_mfma_f32_16x16x32_bf16 v[54:57], v[220:223], v[168:171], v[54:57]
	v_mfma_f32_16x16x32_bf16 v[50:53], v[228:231], v[168:171], v[50:53]
	v_mfma_f32_16x16x32_bf16 v[38:41], v[220:223], v[176:179], v[38:41]
	v_mfma_f32_16x16x32_bf16 v[34:37], v[228:231], v[176:179], v[34:37]
	v_mfma_f32_16x16x32_bf16 v[22:25], v[220:223], v[204:207], v[22:25]
	v_mfma_f32_16x16x32_bf16 v[18:21], v[228:231], v[204:207], v[18:21]
	v_mfma_f32_16x16x32_bf16 v[6:9], v[220:223], v[212:215], v[6:9]
	v_mfma_f32_16x16x32_bf16 v[2:5], v[228:231], v[212:215], v[2:5]
	s_setprio 0
	s_add_i32 s18, 0, 0x18000
	v_add_u32_e32 v151, s18, v149
	s_barrier
	ds_read_b128 v[142:145], v151
	ds_read_b128 v[152:155], v151 offset:1024
	ds_read_b128 v[156:159], v151 offset:2048
	ds_read_b128 v[160:163], v151 offset:3072
	s_add_u32 s4, s4, s2
	s_addc_u32 s5, s5, 0
	s_mov_b32 m0, s24
	v_lshl_add_u64 v[216:217], s[4:5], 0, v[130:131]
	ds_read_b128 v[164:167], v150 offset:32768
	ds_read_b128 v[168:171], v150 offset:33792
	ds_read_b128 v[172:175], v150 offset:34816
	ds_read_b128 v[176:179], v150 offset:35840
	ds_read_b128 v[180:183], v150 offset:36864
	ds_read_b128 v[204:207], v150 offset:37888
	ds_read_b128 v[208:211], v150 offset:38912
	ds_read_b128 v[212:215], v150 offset:39936
	global_load_lds_dwordx4 v[216:217], off
	v_lshl_add_u64 v[216:217], s[4:5], 0, v[134:135]
	s_mov_b32 m0, s25
	s_nop 0
	global_load_lds_dwordx4 v[216:217], off
	s_waitcnt lgkmcnt(8)
	s_barrier
	s_waitcnt lgkmcnt(0)
	s_setprio 1
	s_waitcnt lgkmcnt(0)
	v_mfma_f32_16x16x32_bf16 v[126:129], v[142:145], v[164:167], v[126:129]
	v_mfma_f32_16x16x32_bf16 v[122:125], v[156:159], v[164:167], v[122:125]
	v_mfma_f32_16x16x32_bf16 v[110:113], v[142:145], v[172:175], v[110:113]
	v_mfma_f32_16x16x32_bf16 v[106:109], v[156:159], v[172:175], v[106:109]
	v_mfma_f32_16x16x32_bf16 v[94:97], v[142:145], v[180:183], v[94:97]
	v_mfma_f32_16x16x32_bf16 v[90:93], v[156:159], v[180:183], v[90:93]
	v_mfma_f32_16x16x32_bf16 v[78:81], v[142:145], v[208:211], v[78:81]
	v_mfma_f32_16x16x32_bf16 v[74:77], v[156:159], v[208:211], v[74:77]
	v_mfma_f32_16x16x32_bf16 v[126:129], v[152:155], v[168:171], v[126:129]
	v_mfma_f32_16x16x32_bf16 v[122:125], v[160:163], v[168:171], v[122:125]
	v_mfma_f32_16x16x32_bf16 v[110:113], v[152:155], v[176:179], v[110:113]
	v_mfma_f32_16x16x32_bf16 v[106:109], v[160:163], v[176:179], v[106:109]
	v_mfma_f32_16x16x32_bf16 v[94:97], v[152:155], v[204:207], v[94:97]
	v_mfma_f32_16x16x32_bf16 v[90:93], v[160:163], v[204:207], v[90:93]
	v_mfma_f32_16x16x32_bf16 v[78:81], v[152:155], v[212:215], v[78:81]
	v_mfma_f32_16x16x32_bf16 v[74:77], v[160:163], v[212:215], v[74:77]
	s_setprio 0
	s_barrier
	s_add_i32 s4, 0, 0x1c000
	s_add_i32 s5, s18, s21
	v_add_u32_e32 v151, s4, v149
	v_lshl_add_u64 v[146:147], v[146:147], 0, s[6:7]
	s_mov_b32 m0, s5
	ds_read_b128 v[216:219], v151
	ds_read_b128 v[220:223], v151 offset:1024
	ds_read_b128 v[224:227], v151 offset:2048
	ds_read_b128 v[228:231], v151 offset:3072
	global_load_lds_dwordx4 v[146:147], off
	v_lshl_add_u64 v[146:147], v[184:185], 0, s[6:7]
	s_add_i32 m0, s5, 0x2000
	s_nop 0
	global_load_lds_dwordx4 v[146:147], off
	s_barrier
	s_waitcnt lgkmcnt(0)
	s_setprio 1
	s_waitcnt lgkmcnt(0)
	v_mfma_f32_16x16x32_bf16 v[118:121], v[216:219], v[164:167], v[118:121]
	v_mfma_f32_16x16x32_bf16 v[114:117], v[224:227], v[164:167], v[114:117]
	v_mfma_f32_16x16x32_bf16 v[102:105], v[216:219], v[172:175], v[102:105]
	v_mfma_f32_16x16x32_bf16 v[98:101], v[224:227], v[172:175], v[98:101]
	v_mfma_f32_16x16x32_bf16 v[86:89], v[216:219], v[180:183], v[86:89]
	v_mfma_f32_16x16x32_bf16 v[82:85], v[224:227], v[180:183], v[82:85]
	v_mfma_f32_16x16x32_bf16 v[70:73], v[216:219], v[208:211], v[70:73]
	v_mfma_f32_16x16x32_bf16 v[66:69], v[224:227], v[208:211], v[66:69]
	v_mfma_f32_16x16x32_bf16 v[118:121], v[220:223], v[168:171], v[118:121]
	v_mfma_f32_16x16x32_bf16 v[114:117], v[228:231], v[168:171], v[114:117]
	v_mfma_f32_16x16x32_bf16 v[102:105], v[220:223], v[176:179], v[102:105]
	v_mfma_f32_16x16x32_bf16 v[98:101], v[228:231], v[176:179], v[98:101]
	v_mfma_f32_16x16x32_bf16 v[86:89], v[220:223], v[204:207], v[86:89]
	v_mfma_f32_16x16x32_bf16 v[82:85], v[228:231], v[204:207], v[82:85]
	v_mfma_f32_16x16x32_bf16 v[70:73], v[220:223], v[212:215], v[70:73]
	v_mfma_f32_16x16x32_bf16 v[66:69], v[228:231], v[212:215], v[66:69]
	s_setprio 0
	s_mov_b32 m0, s30
	v_lshl_add_u64 v[146:147], v[232:233], 0, s[6:7]
	s_barrier
	ds_read_b128 v[164:167], v150 offset:49152
	ds_read_b128 v[168:171], v150 offset:50176
	ds_read_b128 v[172:175], v150 offset:51200
	ds_read_b128 v[176:179], v150 offset:52224
	ds_read_b128 v[180:183], v150 offset:53248
	ds_read_b128 v[204:207], v150 offset:54272
	ds_read_b128 v[208:211], v150 offset:55296
	ds_read_b128 v[212:215], v150 offset:56320
	global_load_lds_dwordx4 v[146:147], off
	v_lshl_add_u64 v[146:147], v[234:235], 0, s[6:7]
	s_mov_b32 m0, s31
	s_nop 0
	global_load_lds_dwordx4 v[146:147], off
	s_barrier
	s_waitcnt lgkmcnt(0)
	s_setprio 1
	s_waitcnt lgkmcnt(0)
	v_mfma_f32_16x16x32_bf16 v[62:65], v[142:145], v[164:167], v[62:65]
	v_mfma_f32_16x16x32_bf16 v[58:61], v[156:159], v[164:167], v[58:61]
	v_mfma_f32_16x16x32_bf16 v[46:49], v[142:145], v[172:175], v[46:49]
	v_mfma_f32_16x16x32_bf16 v[42:45], v[156:159], v[172:175], v[42:45]
	v_mfma_f32_16x16x32_bf16 v[30:33], v[142:145], v[180:183], v[30:33]
	v_mfma_f32_16x16x32_bf16 v[26:29], v[156:159], v[180:183], v[26:29]
	v_mfma_f32_16x16x32_bf16 v[14:17], v[142:145], v[208:211], v[14:17]
	v_mfma_f32_16x16x32_bf16 v[10:13], v[156:159], v[208:211], v[10:13]
	v_mfma_f32_16x16x32_bf16 v[62:65], v[152:155], v[168:171], v[62:65]
	v_mfma_f32_16x16x32_bf16 v[58:61], v[160:163], v[168:171], v[58:61]
	v_mfma_f32_16x16x32_bf16 v[46:49], v[152:155], v[176:179], v[46:49]
	v_mfma_f32_16x16x32_bf16 v[42:45], v[160:163], v[176:179], v[42:45]
	v_mfma_f32_16x16x32_bf16 v[30:33], v[152:155], v[204:207], v[30:33]
	v_mfma_f32_16x16x32_bf16 v[26:29], v[160:163], v[204:207], v[26:29]
	v_mfma_f32_16x16x32_bf16 v[14:17], v[152:155], v[212:215], v[14:17]
	v_mfma_f32_16x16x32_bf16 v[10:13], v[160:163], v[212:215], v[10:13]
	s_setprio 0
	s_barrier
	s_add_i32 s4, s4, s21
	v_lshl_add_u64 v[142:143], v[236:237], 0, s[6:7]
	s_mov_b32 m0, s4
	s_nop 0
	global_load_lds_dwordx4 v[142:143], off
	v_lshl_add_u64 v[142:143], v[238:239], 0, s[6:7]
	s_add_i32 m0, s4, 0x2000
	s_nop 0
	global_load_lds_dwordx4 v[142:143], off
	s_waitcnt vmcnt(6)
	s_barrier
	s_setprio 1
	v_mfma_f32_16x16x32_bf16 v[54:57], v[216:219], v[164:167], v[54:57]
	v_mfma_f32_16x16x32_bf16 v[50:53], v[224:227], v[164:167], v[50:53]
	v_mfma_f32_16x16x32_bf16 v[38:41], v[216:219], v[172:175], v[38:41]
	v_mfma_f32_16x16x32_bf16 v[34:37], v[224:227], v[172:175], v[34:37]
	v_mfma_f32_16x16x32_bf16 v[22:25], v[216:219], v[180:183], v[22:25]
	v_mfma_f32_16x16x32_bf16 v[18:21], v[224:227], v[180:183], v[18:21]
	v_mfma_f32_16x16x32_bf16 v[6:9], v[216:219], v[208:211], v[6:9]
	v_mfma_f32_16x16x32_bf16 v[2:5], v[224:227], v[208:211], v[2:5]
	v_mfma_f32_16x16x32_bf16 v[54:57], v[220:223], v[168:171], v[54:57]
	v_mfma_f32_16x16x32_bf16 v[50:53], v[228:231], v[168:171], v[50:53]
	v_mfma_f32_16x16x32_bf16 v[38:41], v[220:223], v[176:179], v[38:41]
	v_mfma_f32_16x16x32_bf16 v[34:37], v[228:231], v[176:179], v[34:37]
	v_mfma_f32_16x16x32_bf16 v[22:25], v[220:223], v[204:207], v[22:25]
	v_mfma_f32_16x16x32_bf16 v[18:21], v[228:231], v[204:207], v[18:21]
	v_mfma_f32_16x16x32_bf16 v[6:9], v[220:223], v[212:215], v[6:9]
	v_mfma_f32_16x16x32_bf16 v[2:5], v[228:231], v[212:215], v[2:5]
	s_setprio 0
	s_add_u32 s0, s0, 0x100
	s_addc_u32 s1, s1, 0
	s_add_u32 s48, s48, 0x100
	s_addc_u32 s49, s49, 0
	s_cmp_ge_u32 s65, s27
	s_mov_b32 s4, s65
	s_barrier
	s_cbranch_scc0 .LBB0_698
	v_mov_b32_e32 v144, v148
	v_mov_b32_e32 v145, v1
	s_lshl_b32 s0, s47, 8
	s_add_i32 s0, s0, s28
	v_add_u32_e32 v153, s0, v144
	v_lshlrev_b32_e32 v144, 2, v144
	s_lshl_b32 s0, s46, 8
	v_lshl_add_u32 v144, v145, 6, v144
	s_or_b32 s0, s0, s29
	v_xor_b32_e32 v152, 64, v144
	v_xor_b32_e32 v151, 0x80, v144
	v_add_u32_e32 v144, s50, v153
	v_lshl_add_u32 v142, v145, 3, s0
	v_cmp_eq_u32_e32 vcc, 0, v145
	v_ashrrev_i32_e32 v145, 31, v144
	v_readlane_b32 s0, v243, 48
	v_lshlrev_b64 v[146:147], 11, v[144:145]
	v_readlane_b32 s1, v243, 49
	v_ashrrev_i32_e32 v143, 31, v142
	s_lshl_b32 s18, s46, 2
	v_lshl_add_u64 v[146:147], s[0:1], 0, v[146:147]
	v_lshl_add_u64 v[146:147], v[142:143], 1, v[146:147]
	v_lshlrev_b32_e32 v159, 11, v148
	v_lshl_add_u32 v159, v142, 1, v159
	s_lshl_b32 s65, s47, 8
	s_add_i32 s65, s65, s28
	s_add_i32 s48, s65, s50
	s_lshl_b32 s48, s48, 11
	s_add_u32 s48, s0, s48
	s_addc_u32 s49, s1, 0
	global_load_dwordx4 v[154:157], v159, s[48:49]
	global_load_dwordx4 v[160:163], v159, s[48:49] offset:256
	s_add_i32 s48, s65, s83
	s_lshl_b32 s48, s48, 11
	s_add_u32 s48, s0, s48
	s_addc_u32 s49, s1, 0
	global_load_dwordx4 v[164:167], v159, s[48:49]
	global_load_dwordx4 v[168:171], v159, s[48:49] offset:256
	s_add_i32 s48, s65, s91
	s_lshl_b32 s48, s48, 11
	s_add_u32 s48, s0, s48
	s_addc_u32 s49, s1, 0
	global_load_dwordx4 v[172:175], v159, s[48:49]
	global_load_dwordx4 v[176:179], v159, s[48:49] offset:256
	s_add_i32 s48, s65, s51
	s_lshl_b32 s48, s48, 11
	s_add_u32 s48, s0, s48
	s_addc_u32 s49, s1, 0
	global_load_dwordx4 v[180:183], v159, s[48:49]
	global_load_dwordx4 v[204:207], v159, s[48:49] offset:256
	s_add_i32 s48, s65, s88
	s_lshl_b32 s48, s48, 11
	s_add_u32 s48, s0, s48
	s_addc_u32 s49, s1, 0
	global_load_dwordx4 v[208:211], v159, s[48:49]
	global_load_dwordx4 v[212:215], v159, s[48:49] offset:256
	s_add_i32 s48, s65, s60
	s_lshl_b32 s48, s48, 11
	s_add_u32 s48, s0, s48
	s_addc_u32 s49, s1, 0
	global_load_dwordx4 v[216:219], v159, s[48:49]
	global_load_dwordx4 v[220:223], v159, s[48:49] offset:256
	s_add_i32 s48, s65, s61
	s_lshl_b32 s48, s48, 11
	s_add_u32 s48, s0, s48
	s_addc_u32 s49, s1, 0
	global_load_dwordx4 v[224:227], v159, s[48:49]
	global_load_dwordx4 v[228:231], v159, s[48:49] offset:256
	s_add_i32 s48, s65, s62
	s_lshl_b32 s48, s48, 11
	s_add_u32 s48, s0, s48
	s_addc_u32 s49, s1, 0
	global_load_dwordx4 v[232:235], v159, s[48:49]
	global_load_dwordx4 v[236:239], v159, s[48:49] offset:256
	s_ashr_i32 s19, s18, 31
	s_waitcnt vmcnt(15)
	v_lshlrev_b32_e32 v158, 16, v154
	v_and_b32_e32 v154, 0xffff0000, v154
	v_add_f32_e32 v127, v127, v154
	v_lshlrev_b32_e32 v154, 16, v155
	v_add_f32_e32 v128, v128, v154
	v_and_b32_e32 v154, 0xffff0000, v155
	v_add_f32_e32 v129, v129, v154
	v_lshlrev_b32_e32 v154, 16, v156
	v_add_f32_e32 v154, v122, v154
	v_and_b32_e32 v122, 0xffff0000, v156
	v_add_f32_e32 v155, v123, v122
	v_lshlrev_b32_e32 v122, 16, v157
	v_add_f32_e32 v156, v124, v122
	v_and_b32_e32 v122, 0xffff0000, v157
	v_add_f32_e32 v126, v126, v158
	v_add_f32_e32 v125, v125, v122
	v_cvt_pk_bf16_f32 v122, v126, v127
	v_cvt_pk_bf16_f32 v123, v128, v129
	v_cvt_pk_bf16_f32 v124, v154, v155
	v_cvt_pk_bf16_f32 v125, v156, v125
	global_store_dwordx4 v[146:147], v[122:125], off
	v_lshlrev_b32_e32 v126, 16, v122
	v_lshlrev_b32_e32 v127, 16, v123
	v_and_b32_e32 v122, 0xffff0000, v122
	v_mul_f32_e32 v154, v122, v122
	v_fmac_f32_e32 v154, v126, v126
	v_and_b32_e32 v123, 0xffff0000, v123
	v_fmac_f32_e32 v154, v127, v127
	v_lshlrev_b32_e32 v128, 16, v124
	v_fmac_f32_e32 v154, v123, v123
	v_and_b32_e32 v124, 0xffff0000, v124
	v_fmac_f32_e32 v154, v128, v128
	v_lshlrev_b32_e32 v129, 16, v125
	v_fmac_f32_e32 v154, v124, v124
	v_and_b32_e32 v125, 0xffff0000, v125
	v_fmac_f32_e32 v154, v129, v129
	v_fmac_f32_e32 v154, v125, v125
	s_waitcnt vmcnt(15)
	v_lshlrev_b32_e32 v126, 16, v160
	v_and_b32_e32 v122, 0xffff0000, v160
	v_add_f32_e32 v119, v119, v122
	v_lshlrev_b32_e32 v122, 16, v161
	v_add_f32_e32 v120, v120, v122
	v_and_b32_e32 v122, 0xffff0000, v161
	v_add_f32_e32 v121, v121, v122
	v_lshlrev_b32_e32 v122, 16, v162
	v_add_f32_e32 v122, v114, v122
	v_and_b32_e32 v114, 0xffff0000, v162
	v_add_f32_e32 v123, v115, v114
	v_lshlrev_b32_e32 v114, 16, v163
	v_add_f32_e32 v124, v116, v114
	v_and_b32_e32 v114, 0xffff0000, v163
	v_add_f32_e32 v118, v118, v126
	v_add_f32_e32 v117, v117, v114
	v_cvt_pk_bf16_f32 v114, v118, v119
	v_cvt_pk_bf16_f32 v115, v120, v121
	v_cvt_pk_bf16_f32 v116, v122, v123
	v_cvt_pk_bf16_f32 v117, v124, v117
	global_store_dwordx4 v[146:147], v[114:117], off offset:256
	v_lshlrev_b32_e32 v118, 16, v114
	v_lshlrev_b32_e32 v119, 16, v115
	v_and_b32_e32 v114, 0xffff0000, v114
	v_mul_f32_e32 v114, v114, v114
	v_fmac_f32_e32 v114, v118, v118
	v_and_b32_e32 v115, 0xffff0000, v115
	v_fmac_f32_e32 v114, v119, v119
	v_lshlrev_b32_e32 v120, 16, v116
	v_fmac_f32_e32 v114, v115, v115
	v_and_b32_e32 v116, 0xffff0000, v116
	v_fmac_f32_e32 v114, v120, v120
	v_lshlrev_b32_e32 v121, 16, v117
	v_fmac_f32_e32 v114, v116, v116
	v_and_b32_e32 v117, 0xffff0000, v117
	v_fmac_f32_e32 v114, v121, v121
	v_fmac_f32_e32 v114, v117, v117
	v_add_f32_e32 v114, v154, v114
	ds_bpermute_b32 v115, v152, v114
	s_waitcnt lgkmcnt(0)
	v_add_f32_e32 v114, v114, v115
	ds_bpermute_b32 v115, v151, v114
	s_and_saveexec_b64 s[0:1], vcc
	s_cbranch_execz .LBB0_701
	v_readlane_b32 s4, v242, 3
	s_waitcnt lgkmcnt(0)
	v_add_f32_e32 v116, v114, v115
	v_lshlrev_b64 v[114:115], 6, v[144:145]
	v_readlane_b32 s5, v242, 4
	s_lshl_b32 s92, s26, 2
	s_nop 0
	v_lshl_add_u64 v[114:115], s[4:5], 0, v[114:115]
	v_lshl_add_u64 v[114:115], s[18:19], 2, v[114:115]
	v_lshl_add_u64 v[114:115], v[114:115], 0, s[92:93]
	global_store_dword v[114:115], v116, off
.LBB0_701:
	s_or_b64 exec, exec, s[0:1]
	v_add_u32_e32 v114, s83, v153
	s_waitcnt lgkmcnt(0)
	v_ashrrev_i32_e32 v115, 31, v114
	v_readlane_b32 s0, v243, 48
	v_lshlrev_b64 v[116:117], 11, v[114:115]
	v_readlane_b32 s1, v243, 49
	s_nop 1
	v_lshl_add_u64 v[116:117], s[0:1], 0, v[116:117]
	v_lshl_add_u64 v[116:117], v[142:143], 1, v[116:117]
	s_waitcnt vmcnt(16)
	v_lshlrev_b32_e32 v122, 16, v164
	v_and_b32_e32 v118, 0xffff0000, v164
	v_add_f32_e32 v111, v111, v118
	v_lshlrev_b32_e32 v118, 16, v165
	v_add_f32_e32 v112, v112, v118
	v_and_b32_e32 v118, 0xffff0000, v165
	v_add_f32_e32 v113, v113, v118
	v_lshlrev_b32_e32 v118, 16, v166
	v_add_f32_e32 v118, v106, v118
	v_and_b32_e32 v106, 0xffff0000, v166
	v_add_f32_e32 v119, v107, v106
	v_lshlrev_b32_e32 v106, 16, v167
	v_add_f32_e32 v120, v108, v106
	v_and_b32_e32 v106, 0xffff0000, v167
	v_add_f32_e32 v110, v110, v122
	v_add_f32_e32 v109, v109, v106
	v_cvt_pk_bf16_f32 v106, v110, v111
	v_cvt_pk_bf16_f32 v107, v112, v113
	v_cvt_pk_bf16_f32 v108, v118, v119
	v_cvt_pk_bf16_f32 v109, v120, v109
	global_store_dwordx4 v[116:117], v[106:109], off
	v_lshlrev_b32_e32 v110, 16, v106
	v_lshlrev_b32_e32 v111, 16, v107
	v_and_b32_e32 v106, 0xffff0000, v106
	v_mul_f32_e32 v118, v106, v106
	v_fmac_f32_e32 v118, v110, v110
	v_and_b32_e32 v107, 0xffff0000, v107
	v_fmac_f32_e32 v118, v111, v111
	v_lshlrev_b32_e32 v112, 16, v108
	v_fmac_f32_e32 v118, v107, v107
	v_and_b32_e32 v108, 0xffff0000, v108
	v_fmac_f32_e32 v118, v112, v112
	v_lshlrev_b32_e32 v113, 16, v109
	v_fmac_f32_e32 v118, v108, v108
	v_and_b32_e32 v109, 0xffff0000, v109
	v_fmac_f32_e32 v118, v113, v113
	v_fmac_f32_e32 v118, v109, v109
	s_waitcnt vmcnt(16)
	v_lshlrev_b32_e32 v110, 16, v168
	v_and_b32_e32 v106, 0xffff0000, v168
	v_add_f32_e32 v103, v103, v106
	v_lshlrev_b32_e32 v106, 16, v169
	v_add_f32_e32 v104, v104, v106
	v_and_b32_e32 v106, 0xffff0000, v169
	v_add_f32_e32 v105, v105, v106
	v_lshlrev_b32_e32 v106, 16, v170
	v_add_f32_e32 v106, v98, v106
	v_and_b32_e32 v98, 0xffff0000, v170
	v_add_f32_e32 v107, v99, v98
	v_lshlrev_b32_e32 v98, 16, v171
	v_add_f32_e32 v108, v100, v98
	v_and_b32_e32 v98, 0xffff0000, v171
	v_add_f32_e32 v102, v102, v110
	v_add_f32_e32 v101, v101, v98
	v_cvt_pk_bf16_f32 v98, v102, v103
	v_cvt_pk_bf16_f32 v99, v104, v105
	v_cvt_pk_bf16_f32 v100, v106, v107
	v_cvt_pk_bf16_f32 v101, v108, v101
	global_store_dwordx4 v[116:117], v[98:101], off offset:256
	v_lshlrev_b32_e32 v102, 16, v98
	v_lshlrev_b32_e32 v103, 16, v99
	v_and_b32_e32 v98, 0xffff0000, v98
	v_mul_f32_e32 v98, v98, v98
	v_fmac_f32_e32 v98, v102, v102
	v_and_b32_e32 v99, 0xffff0000, v99
	v_fmac_f32_e32 v98, v103, v103
	v_lshlrev_b32_e32 v104, 16, v100
	v_fmac_f32_e32 v98, v99, v99
	v_and_b32_e32 v100, 0xffff0000, v100
	v_fmac_f32_e32 v98, v104, v104
	v_lshlrev_b32_e32 v105, 16, v101
	v_fmac_f32_e32 v98, v100, v100
	v_and_b32_e32 v101, 0xffff0000, v101
	v_fmac_f32_e32 v98, v105, v105
	v_fmac_f32_e32 v98, v101, v101
	v_add_f32_e32 v98, v118, v98
	ds_bpermute_b32 v99, v152, v98
	s_waitcnt lgkmcnt(0)
	v_add_f32_e32 v98, v98, v99
	ds_bpermute_b32 v99, v151, v98
	s_and_saveexec_b64 s[0:1], vcc
	s_cbranch_execz .LBB0_703
	v_readlane_b32 s4, v242, 3
	s_waitcnt lgkmcnt(0)
	v_add_f32_e32 v100, v98, v99
	v_lshlrev_b64 v[98:99], 6, v[114:115]
	v_readlane_b32 s5, v242, 4
	s_lshl_b32 s92, s26, 2
	s_nop 0
	v_lshl_add_u64 v[98:99], s[4:5], 0, v[98:99]
	v_lshl_add_u64 v[98:99], s[18:19], 2, v[98:99]
	v_lshl_add_u64 v[98:99], v[98:99], 0, s[92:93]
	global_store_dword v[98:99], v100, off
.LBB0_703:
	s_or_b64 exec, exec, s[0:1]
	v_add_u32_e32 v98, s91, v153
	s_waitcnt lgkmcnt(0)
	v_ashrrev_i32_e32 v99, 31, v98
	v_readlane_b32 s0, v243, 48
	v_lshlrev_b64 v[100:101], 11, v[98:99]
	v_readlane_b32 s1, v243, 49
	s_nop 1
	v_lshl_add_u64 v[100:101], s[0:1], 0, v[100:101]
	v_lshl_add_u64 v[100:101], v[142:143], 1, v[100:101]
	s_waitcnt vmcnt(17)
	v_lshlrev_b32_e32 v106, 16, v172
	v_and_b32_e32 v102, 0xffff0000, v172
	v_add_f32_e32 v95, v95, v102
	v_lshlrev_b32_e32 v102, 16, v173
	v_add_f32_e32 v96, v96, v102
	v_and_b32_e32 v102, 0xffff0000, v173
	v_add_f32_e32 v97, v97, v102
	v_lshlrev_b32_e32 v102, 16, v174
	v_add_f32_e32 v102, v90, v102
	v_and_b32_e32 v90, 0xffff0000, v174
	v_add_f32_e32 v103, v91, v90
	v_lshlrev_b32_e32 v90, 16, v175
	v_add_f32_e32 v104, v92, v90
	v_and_b32_e32 v90, 0xffff0000, v175
	v_add_f32_e32 v94, v94, v106
	v_add_f32_e32 v93, v93, v90
	v_cvt_pk_bf16_f32 v90, v94, v95
	v_cvt_pk_bf16_f32 v91, v96, v97
	v_cvt_pk_bf16_f32 v92, v102, v103
	v_cvt_pk_bf16_f32 v93, v104, v93
	global_store_dwordx4 v[100:101], v[90:93], off
	v_lshlrev_b32_e32 v94, 16, v90
	v_lshlrev_b32_e32 v95, 16, v91
	v_and_b32_e32 v90, 0xffff0000, v90
	v_mul_f32_e32 v102, v90, v90
	v_fmac_f32_e32 v102, v94, v94
	v_and_b32_e32 v91, 0xffff0000, v91
	v_fmac_f32_e32 v102, v95, v95
	v_lshlrev_b32_e32 v96, 16, v92
	v_fmac_f32_e32 v102, v91, v91
	v_and_b32_e32 v92, 0xffff0000, v92
	v_fmac_f32_e32 v102, v96, v96
	v_lshlrev_b32_e32 v97, 16, v93
	v_fmac_f32_e32 v102, v92, v92
	v_and_b32_e32 v93, 0xffff0000, v93
	v_fmac_f32_e32 v102, v97, v97
	v_fmac_f32_e32 v102, v93, v93
	s_waitcnt vmcnt(17)
	v_lshlrev_b32_e32 v94, 16, v176
	v_and_b32_e32 v90, 0xffff0000, v176
	v_add_f32_e32 v87, v87, v90
	v_lshlrev_b32_e32 v90, 16, v177
	v_add_f32_e32 v88, v88, v90
	v_and_b32_e32 v90, 0xffff0000, v177
	v_add_f32_e32 v89, v89, v90
	v_lshlrev_b32_e32 v90, 16, v178
	v_add_f32_e32 v90, v82, v90
	v_and_b32_e32 v82, 0xffff0000, v178
	v_add_f32_e32 v91, v83, v82
	v_lshlrev_b32_e32 v82, 16, v179
	v_add_f32_e32 v92, v84, v82
	v_and_b32_e32 v82, 0xffff0000, v179
	v_add_f32_e32 v86, v86, v94
	v_add_f32_e32 v85, v85, v82
	v_cvt_pk_bf16_f32 v82, v86, v87
	v_cvt_pk_bf16_f32 v83, v88, v89
	v_cvt_pk_bf16_f32 v84, v90, v91
	v_cvt_pk_bf16_f32 v85, v92, v85
	global_store_dwordx4 v[100:101], v[82:85], off offset:256
	v_lshlrev_b32_e32 v86, 16, v82
	v_lshlrev_b32_e32 v87, 16, v83
	v_and_b32_e32 v82, 0xffff0000, v82
	v_mul_f32_e32 v82, v82, v82
	v_fmac_f32_e32 v82, v86, v86
	v_and_b32_e32 v83, 0xffff0000, v83
	v_fmac_f32_e32 v82, v87, v87
	v_lshlrev_b32_e32 v88, 16, v84
	v_fmac_f32_e32 v82, v83, v83
	v_and_b32_e32 v84, 0xffff0000, v84
	v_fmac_f32_e32 v82, v88, v88
	v_lshlrev_b32_e32 v89, 16, v85
	v_fmac_f32_e32 v82, v84, v84
	v_and_b32_e32 v85, 0xffff0000, v85
	v_fmac_f32_e32 v82, v89, v89
	v_fmac_f32_e32 v82, v85, v85
	v_add_f32_e32 v82, v102, v82
	ds_bpermute_b32 v83, v152, v82
	s_waitcnt lgkmcnt(0)
	v_add_f32_e32 v82, v82, v83
	ds_bpermute_b32 v83, v151, v82
	s_and_saveexec_b64 s[0:1], vcc
	s_cbranch_execz .LBB0_705
	v_readlane_b32 s4, v242, 3
	s_waitcnt lgkmcnt(0)
	v_add_f32_e32 v84, v82, v83
	v_lshlrev_b64 v[82:83], 6, v[98:99]
	v_readlane_b32 s5, v242, 4
	s_lshl_b32 s92, s26, 2
	s_nop 0
	v_lshl_add_u64 v[82:83], s[4:5], 0, v[82:83]
	v_lshl_add_u64 v[82:83], s[18:19], 2, v[82:83]
	v_lshl_add_u64 v[82:83], v[82:83], 0, s[92:93]
	global_store_dword v[82:83], v84, off
.LBB0_705:
	s_or_b64 exec, exec, s[0:1]
	v_add_u32_e32 v82, s51, v153
	s_waitcnt lgkmcnt(0)
	v_ashrrev_i32_e32 v83, 31, v82
	v_readlane_b32 s0, v243, 48
	v_lshlrev_b64 v[84:85], 11, v[82:83]
	v_readlane_b32 s1, v243, 49
	s_nop 1
	v_lshl_add_u64 v[84:85], s[0:1], 0, v[84:85]
	v_lshl_add_u64 v[84:85], v[142:143], 1, v[84:85]
	s_waitcnt vmcnt(18)
	v_lshlrev_b32_e32 v90, 16, v180
	v_and_b32_e32 v86, 0xffff0000, v180
	v_add_f32_e32 v79, v79, v86
	v_lshlrev_b32_e32 v86, 16, v181
	v_add_f32_e32 v80, v80, v86
	v_and_b32_e32 v86, 0xffff0000, v181
	v_add_f32_e32 v81, v81, v86
	v_lshlrev_b32_e32 v86, 16, v182
	v_add_f32_e32 v86, v74, v86
	v_and_b32_e32 v74, 0xffff0000, v182
	v_add_f32_e32 v87, v75, v74
	v_lshlrev_b32_e32 v74, 16, v183
	v_add_f32_e32 v88, v76, v74
	v_and_b32_e32 v74, 0xffff0000, v183
	v_add_f32_e32 v78, v78, v90
	v_add_f32_e32 v77, v77, v74
	v_cvt_pk_bf16_f32 v74, v78, v79
	v_cvt_pk_bf16_f32 v75, v80, v81
	v_cvt_pk_bf16_f32 v76, v86, v87
	v_cvt_pk_bf16_f32 v77, v88, v77
	global_store_dwordx4 v[84:85], v[74:77], off
	v_lshlrev_b32_e32 v78, 16, v74
	v_lshlrev_b32_e32 v79, 16, v75
	v_and_b32_e32 v74, 0xffff0000, v74
	v_mul_f32_e32 v86, v74, v74
	v_fmac_f32_e32 v86, v78, v78
	v_and_b32_e32 v75, 0xffff0000, v75
	v_fmac_f32_e32 v86, v79, v79
	v_lshlrev_b32_e32 v80, 16, v76
	v_fmac_f32_e32 v86, v75, v75
	v_and_b32_e32 v76, 0xffff0000, v76
	v_fmac_f32_e32 v86, v80, v80
	v_lshlrev_b32_e32 v81, 16, v77
	v_fmac_f32_e32 v86, v76, v76
	v_and_b32_e32 v77, 0xffff0000, v77
	v_fmac_f32_e32 v86, v81, v81
	v_fmac_f32_e32 v86, v77, v77
	s_waitcnt vmcnt(18)
	v_lshlrev_b32_e32 v78, 16, v204
	v_and_b32_e32 v74, 0xffff0000, v204
	v_add_f32_e32 v71, v71, v74
	v_lshlrev_b32_e32 v74, 16, v205
	v_add_f32_e32 v72, v72, v74
	v_and_b32_e32 v74, 0xffff0000, v205
	v_add_f32_e32 v73, v73, v74
	v_lshlrev_b32_e32 v74, 16, v206
	v_add_f32_e32 v74, v66, v74
	v_and_b32_e32 v66, 0xffff0000, v206
	v_add_f32_e32 v75, v67, v66
	v_lshlrev_b32_e32 v66, 16, v207
	v_add_f32_e32 v76, v68, v66
	v_and_b32_e32 v66, 0xffff0000, v207
	v_add_f32_e32 v70, v70, v78
	v_add_f32_e32 v69, v69, v66
	v_cvt_pk_bf16_f32 v66, v70, v71
	v_cvt_pk_bf16_f32 v67, v72, v73
	v_cvt_pk_bf16_f32 v68, v74, v75
	v_cvt_pk_bf16_f32 v69, v76, v69
	global_store_dwordx4 v[84:85], v[66:69], off offset:256
	v_lshlrev_b32_e32 v70, 16, v66
	v_lshlrev_b32_e32 v71, 16, v67
	v_and_b32_e32 v66, 0xffff0000, v66
	v_mul_f32_e32 v66, v66, v66
	v_fmac_f32_e32 v66, v70, v70
	v_and_b32_e32 v67, 0xffff0000, v67
	v_fmac_f32_e32 v66, v71, v71
	v_lshlrev_b32_e32 v72, 16, v68
	v_fmac_f32_e32 v66, v67, v67
	v_and_b32_e32 v68, 0xffff0000, v68
	v_fmac_f32_e32 v66, v72, v72
	v_lshlrev_b32_e32 v73, 16, v69
	v_fmac_f32_e32 v66, v68, v68
	v_and_b32_e32 v69, 0xffff0000, v69
	v_fmac_f32_e32 v66, v73, v73
	v_fmac_f32_e32 v66, v69, v69
	v_add_f32_e32 v66, v86, v66
	ds_bpermute_b32 v67, v152, v66
	s_waitcnt lgkmcnt(0)
	v_add_f32_e32 v66, v66, v67
	ds_bpermute_b32 v67, v151, v66
	s_and_saveexec_b64 s[0:1], vcc
	s_cbranch_execz .LBB0_707
	v_readlane_b32 s4, v242, 3
	s_waitcnt lgkmcnt(0)
	v_add_f32_e32 v68, v66, v67
	v_lshlrev_b64 v[66:67], 6, v[82:83]
	v_readlane_b32 s5, v242, 4
	s_lshl_b32 s92, s26, 2
	s_nop 0
	v_lshl_add_u64 v[66:67], s[4:5], 0, v[66:67]
	v_lshl_add_u64 v[66:67], s[18:19], 2, v[66:67]
	v_lshl_add_u64 v[66:67], v[66:67], 0, s[92:93]
	global_store_dword v[66:67], v68, off
.LBB0_707:
	s_or_b64 exec, exec, s[0:1]
	v_add_u32_e32 v66, s88, v153
	s_waitcnt lgkmcnt(0)
	v_ashrrev_i32_e32 v67, 31, v66
	v_readlane_b32 s0, v243, 48
	v_lshlrev_b64 v[68:69], 11, v[66:67]
	v_readlane_b32 s1, v243, 49
	s_nop 1
	v_lshl_add_u64 v[68:69], s[0:1], 0, v[68:69]
	v_lshl_add_u64 v[68:69], v[142:143], 1, v[68:69]
	s_waitcnt vmcnt(19)
	v_lshlrev_b32_e32 v74, 16, v208
	v_and_b32_e32 v70, 0xffff0000, v208
	v_add_f32_e32 v63, v63, v70
	v_lshlrev_b32_e32 v70, 16, v209
	v_add_f32_e32 v64, v64, v70
	v_and_b32_e32 v70, 0xffff0000, v209
	v_add_f32_e32 v65, v65, v70
	v_lshlrev_b32_e32 v70, 16, v210
	v_add_f32_e32 v70, v58, v70
	v_and_b32_e32 v58, 0xffff0000, v210
	v_add_f32_e32 v71, v59, v58
	v_lshlrev_b32_e32 v58, 16, v211
	v_add_f32_e32 v72, v60, v58
	v_and_b32_e32 v58, 0xffff0000, v211
	v_add_f32_e32 v62, v62, v74
	v_add_f32_e32 v61, v61, v58
	v_cvt_pk_bf16_f32 v58, v62, v63
	v_cvt_pk_bf16_f32 v59, v64, v65
	v_cvt_pk_bf16_f32 v60, v70, v71
	v_cvt_pk_bf16_f32 v61, v72, v61
	global_store_dwordx4 v[68:69], v[58:61], off
	v_lshlrev_b32_e32 v62, 16, v58
	v_lshlrev_b32_e32 v63, 16, v59
	v_and_b32_e32 v58, 0xffff0000, v58
	v_mul_f32_e32 v70, v58, v58
	v_fmac_f32_e32 v70, v62, v62
	v_and_b32_e32 v59, 0xffff0000, v59
	v_fmac_f32_e32 v70, v63, v63
	v_lshlrev_b32_e32 v64, 16, v60
	v_fmac_f32_e32 v70, v59, v59
	v_and_b32_e32 v60, 0xffff0000, v60
	v_fmac_f32_e32 v70, v64, v64
	v_lshlrev_b32_e32 v65, 16, v61
	v_fmac_f32_e32 v70, v60, v60
	v_and_b32_e32 v61, 0xffff0000, v61
	v_fmac_f32_e32 v70, v65, v65
	v_fmac_f32_e32 v70, v61, v61
	s_waitcnt vmcnt(19)
	v_lshlrev_b32_e32 v62, 16, v212
	v_and_b32_e32 v58, 0xffff0000, v212
	v_add_f32_e32 v55, v55, v58
	v_lshlrev_b32_e32 v58, 16, v213
	v_add_f32_e32 v56, v56, v58
	v_and_b32_e32 v58, 0xffff0000, v213
	v_add_f32_e32 v57, v57, v58
	v_lshlrev_b32_e32 v58, 16, v214
	v_add_f32_e32 v58, v50, v58
	v_and_b32_e32 v50, 0xffff0000, v214
	v_add_f32_e32 v59, v51, v50
	v_lshlrev_b32_e32 v50, 16, v215
	v_add_f32_e32 v60, v52, v50
	v_and_b32_e32 v50, 0xffff0000, v215
	v_add_f32_e32 v54, v54, v62
	v_add_f32_e32 v53, v53, v50
	v_cvt_pk_bf16_f32 v50, v54, v55
	v_cvt_pk_bf16_f32 v51, v56, v57
	v_cvt_pk_bf16_f32 v52, v58, v59
	v_cvt_pk_bf16_f32 v53, v60, v53
	global_store_dwordx4 v[68:69], v[50:53], off offset:256
	v_lshlrev_b32_e32 v54, 16, v50
	v_lshlrev_b32_e32 v55, 16, v51
	v_and_b32_e32 v50, 0xffff0000, v50
	v_mul_f32_e32 v50, v50, v50
	v_fmac_f32_e32 v50, v54, v54
	v_and_b32_e32 v51, 0xffff0000, v51
	v_fmac_f32_e32 v50, v55, v55
	v_lshlrev_b32_e32 v56, 16, v52
	v_fmac_f32_e32 v50, v51, v51
	v_and_b32_e32 v52, 0xffff0000, v52
	v_fmac_f32_e32 v50, v56, v56
	v_lshlrev_b32_e32 v57, 16, v53
	v_fmac_f32_e32 v50, v52, v52
	v_and_b32_e32 v53, 0xffff0000, v53
	v_fmac_f32_e32 v50, v57, v57
	v_fmac_f32_e32 v50, v53, v53
	v_add_f32_e32 v50, v70, v50
	ds_bpermute_b32 v51, v152, v50
	s_waitcnt lgkmcnt(0)
	v_add_f32_e32 v50, v50, v51
	ds_bpermute_b32 v51, v151, v50
	s_and_saveexec_b64 s[0:1], vcc
	s_cbranch_execz .LBB0_709
	v_readlane_b32 s4, v242, 3
	s_waitcnt lgkmcnt(0)
	v_add_f32_e32 v52, v50, v51
	v_lshlrev_b64 v[50:51], 6, v[66:67]
	v_readlane_b32 s5, v242, 4
	s_lshl_b32 s92, s26, 2
	s_nop 0
	v_lshl_add_u64 v[50:51], s[4:5], 0, v[50:51]
	v_lshl_add_u64 v[50:51], s[18:19], 2, v[50:51]
	v_lshl_add_u64 v[50:51], v[50:51], 0, s[92:93]
	global_store_dword v[50:51], v52, off
.LBB0_709:
	s_or_b64 exec, exec, s[0:1]
	v_add_u32_e32 v50, s60, v153
	s_waitcnt lgkmcnt(0)
	v_ashrrev_i32_e32 v51, 31, v50
	v_readlane_b32 s0, v243, 48
	v_lshlrev_b64 v[52:53], 11, v[50:51]
	v_readlane_b32 s1, v243, 49
	s_nop 1
	v_lshl_add_u64 v[52:53], s[0:1], 0, v[52:53]
	v_lshl_add_u64 v[52:53], v[142:143], 1, v[52:53]
	s_waitcnt vmcnt(20)
	v_lshlrev_b32_e32 v58, 16, v216
	v_and_b32_e32 v54, 0xffff0000, v216
	v_add_f32_e32 v47, v47, v54
	v_lshlrev_b32_e32 v54, 16, v217
	v_add_f32_e32 v48, v48, v54
	v_and_b32_e32 v54, 0xffff0000, v217
	v_add_f32_e32 v49, v49, v54
	v_lshlrev_b32_e32 v54, 16, v218
	v_add_f32_e32 v54, v42, v54
	v_and_b32_e32 v42, 0xffff0000, v218
	v_add_f32_e32 v55, v43, v42
	v_lshlrev_b32_e32 v42, 16, v219
	v_add_f32_e32 v56, v44, v42
	v_and_b32_e32 v42, 0xffff0000, v219
	v_add_f32_e32 v46, v46, v58
	v_add_f32_e32 v45, v45, v42
	v_cvt_pk_bf16_f32 v42, v46, v47
	v_cvt_pk_bf16_f32 v43, v48, v49
	v_cvt_pk_bf16_f32 v44, v54, v55
	v_cvt_pk_bf16_f32 v45, v56, v45
	global_store_dwordx4 v[52:53], v[42:45], off
	v_lshlrev_b32_e32 v46, 16, v42
	v_lshlrev_b32_e32 v47, 16, v43
	v_and_b32_e32 v42, 0xffff0000, v42
	v_mul_f32_e32 v54, v42, v42
	v_fmac_f32_e32 v54, v46, v46
	v_and_b32_e32 v43, 0xffff0000, v43
	v_fmac_f32_e32 v54, v47, v47
	v_lshlrev_b32_e32 v48, 16, v44
	v_fmac_f32_e32 v54, v43, v43
	v_and_b32_e32 v44, 0xffff0000, v44
	v_fmac_f32_e32 v54, v48, v48
	v_lshlrev_b32_e32 v49, 16, v45
	v_fmac_f32_e32 v54, v44, v44
	v_and_b32_e32 v45, 0xffff0000, v45
	v_fmac_f32_e32 v54, v49, v49
	v_fmac_f32_e32 v54, v45, v45
	s_waitcnt vmcnt(20)
	v_lshlrev_b32_e32 v46, 16, v220
	v_and_b32_e32 v42, 0xffff0000, v220
	v_add_f32_e32 v39, v39, v42
	v_lshlrev_b32_e32 v42, 16, v221
	v_add_f32_e32 v40, v40, v42
	v_and_b32_e32 v42, 0xffff0000, v221
	v_add_f32_e32 v41, v41, v42
	v_lshlrev_b32_e32 v42, 16, v222
	v_add_f32_e32 v42, v34, v42
	v_and_b32_e32 v34, 0xffff0000, v222
	v_add_f32_e32 v43, v35, v34
	v_lshlrev_b32_e32 v34, 16, v223
	v_add_f32_e32 v44, v36, v34
	v_and_b32_e32 v34, 0xffff0000, v223
	v_add_f32_e32 v38, v38, v46
	v_add_f32_e32 v37, v37, v34
	v_cvt_pk_bf16_f32 v34, v38, v39
	v_cvt_pk_bf16_f32 v35, v40, v41
	v_cvt_pk_bf16_f32 v36, v42, v43
	v_cvt_pk_bf16_f32 v37, v44, v37
	global_store_dwordx4 v[52:53], v[34:37], off offset:256
	v_lshlrev_b32_e32 v38, 16, v34
	v_lshlrev_b32_e32 v39, 16, v35
	v_and_b32_e32 v34, 0xffff0000, v34
	v_mul_f32_e32 v34, v34, v34
	v_fmac_f32_e32 v34, v38, v38
	v_and_b32_e32 v35, 0xffff0000, v35
	v_fmac_f32_e32 v34, v39, v39
	v_lshlrev_b32_e32 v40, 16, v36
	v_fmac_f32_e32 v34, v35, v35
	v_and_b32_e32 v36, 0xffff0000, v36
	v_fmac_f32_e32 v34, v40, v40
	v_lshlrev_b32_e32 v41, 16, v37
	v_fmac_f32_e32 v34, v36, v36
	v_and_b32_e32 v37, 0xffff0000, v37
	v_fmac_f32_e32 v34, v41, v41
	v_fmac_f32_e32 v34, v37, v37
	v_add_f32_e32 v34, v54, v34
	ds_bpermute_b32 v35, v152, v34
	s_waitcnt lgkmcnt(0)
	v_add_f32_e32 v34, v34, v35
	ds_bpermute_b32 v35, v151, v34
	s_and_saveexec_b64 s[0:1], vcc
	s_cbranch_execz .LBB0_711
	v_readlane_b32 s4, v242, 3
	s_waitcnt lgkmcnt(0)
	v_add_f32_e32 v36, v34, v35
	v_lshlrev_b64 v[34:35], 6, v[50:51]
	v_readlane_b32 s5, v242, 4
	s_lshl_b32 s92, s26, 2
	s_nop 0
	v_lshl_add_u64 v[34:35], s[4:5], 0, v[34:35]
	v_lshl_add_u64 v[34:35], s[18:19], 2, v[34:35]
	v_lshl_add_u64 v[34:35], v[34:35], 0, s[92:93]
	global_store_dword v[34:35], v36, off
.LBB0_711:
	s_or_b64 exec, exec, s[0:1]
	v_add_u32_e32 v34, s61, v153
	s_waitcnt lgkmcnt(0)
	v_ashrrev_i32_e32 v35, 31, v34
	v_readlane_b32 s0, v243, 48
	v_lshlrev_b64 v[36:37], 11, v[34:35]
	v_readlane_b32 s1, v243, 49
	s_nop 1
	v_lshl_add_u64 v[36:37], s[0:1], 0, v[36:37]
	v_lshl_add_u64 v[36:37], v[142:143], 1, v[36:37]
	s_waitcnt vmcnt(21)
	v_lshlrev_b32_e32 v42, 16, v224
	v_and_b32_e32 v38, 0xffff0000, v224
	v_add_f32_e32 v31, v31, v38
	v_lshlrev_b32_e32 v38, 16, v225
	v_add_f32_e32 v32, v32, v38
	v_and_b32_e32 v38, 0xffff0000, v225
	v_add_f32_e32 v33, v33, v38
	v_lshlrev_b32_e32 v38, 16, v226
	v_add_f32_e32 v38, v26, v38
	v_and_b32_e32 v26, 0xffff0000, v226
	v_add_f32_e32 v39, v27, v26
	v_lshlrev_b32_e32 v26, 16, v227
	v_add_f32_e32 v40, v28, v26
	v_and_b32_e32 v26, 0xffff0000, v227
	v_add_f32_e32 v30, v30, v42
	v_add_f32_e32 v29, v29, v26
	v_cvt_pk_bf16_f32 v26, v30, v31
	v_cvt_pk_bf16_f32 v27, v32, v33
	v_cvt_pk_bf16_f32 v28, v38, v39
	v_cvt_pk_bf16_f32 v29, v40, v29
	global_store_dwordx4 v[36:37], v[26:29], off
	v_lshlrev_b32_e32 v30, 16, v26
	v_lshlrev_b32_e32 v31, 16, v27
	v_and_b32_e32 v26, 0xffff0000, v26
	v_mul_f32_e32 v38, v26, v26
	v_fmac_f32_e32 v38, v30, v30
	v_and_b32_e32 v27, 0xffff0000, v27
	v_fmac_f32_e32 v38, v31, v31
	v_lshlrev_b32_e32 v32, 16, v28
	v_fmac_f32_e32 v38, v27, v27
	v_and_b32_e32 v28, 0xffff0000, v28
	v_fmac_f32_e32 v38, v32, v32
	v_lshlrev_b32_e32 v33, 16, v29
	v_fmac_f32_e32 v38, v28, v28
	v_and_b32_e32 v29, 0xffff0000, v29
	v_fmac_f32_e32 v38, v33, v33
	v_fmac_f32_e32 v38, v29, v29
	s_waitcnt vmcnt(21)
	v_lshlrev_b32_e32 v30, 16, v228
	v_and_b32_e32 v26, 0xffff0000, v228
	v_add_f32_e32 v23, v23, v26
	v_lshlrev_b32_e32 v26, 16, v229
	v_add_f32_e32 v24, v24, v26
	v_and_b32_e32 v26, 0xffff0000, v229
	v_add_f32_e32 v25, v25, v26
	v_lshlrev_b32_e32 v26, 16, v230
	v_add_f32_e32 v26, v18, v26
	v_and_b32_e32 v18, 0xffff0000, v230
	v_add_f32_e32 v27, v19, v18
	v_lshlrev_b32_e32 v18, 16, v231
	v_add_f32_e32 v28, v20, v18
	v_and_b32_e32 v18, 0xffff0000, v231
	v_add_f32_e32 v22, v22, v30
	v_add_f32_e32 v21, v21, v18
	v_cvt_pk_bf16_f32 v18, v22, v23
	v_cvt_pk_bf16_f32 v19, v24, v25
	v_cvt_pk_bf16_f32 v20, v26, v27
	v_cvt_pk_bf16_f32 v21, v28, v21
	global_store_dwordx4 v[36:37], v[18:21], off offset:256
	v_lshlrev_b32_e32 v22, 16, v18
	v_lshlrev_b32_e32 v23, 16, v19
	v_and_b32_e32 v18, 0xffff0000, v18
	v_mul_f32_e32 v18, v18, v18
	v_fmac_f32_e32 v18, v22, v22
	v_and_b32_e32 v19, 0xffff0000, v19
	v_fmac_f32_e32 v18, v23, v23
	v_lshlrev_b32_e32 v24, 16, v20
	v_fmac_f32_e32 v18, v19, v19
	v_and_b32_e32 v20, 0xffff0000, v20
	v_fmac_f32_e32 v18, v24, v24
	v_lshlrev_b32_e32 v25, 16, v21
	v_fmac_f32_e32 v18, v20, v20
	v_and_b32_e32 v21, 0xffff0000, v21
	v_fmac_f32_e32 v18, v25, v25
	v_fmac_f32_e32 v18, v21, v21
	v_add_f32_e32 v18, v38, v18
	ds_bpermute_b32 v19, v152, v18
	s_waitcnt lgkmcnt(0)
	v_add_f32_e32 v18, v18, v19
	ds_bpermute_b32 v19, v151, v18
	s_and_saveexec_b64 s[0:1], vcc
	s_cbranch_execz .LBB0_713
	v_readlane_b32 s4, v242, 3
	s_waitcnt lgkmcnt(0)
	v_add_f32_e32 v20, v18, v19
	v_lshlrev_b64 v[18:19], 6, v[34:35]
	v_readlane_b32 s5, v242, 4
	s_lshl_b32 s92, s26, 2
	s_nop 0
	v_lshl_add_u64 v[18:19], s[4:5], 0, v[18:19]
	v_lshl_add_u64 v[18:19], s[18:19], 2, v[18:19]
	v_lshl_add_u64 v[18:19], v[18:19], 0, s[92:93]
	global_store_dword v[18:19], v20, off
.LBB0_713:
	s_or_b64 exec, exec, s[0:1]
	v_add_u32_e32 v18, s62, v153
	s_waitcnt lgkmcnt(0)
	v_ashrrev_i32_e32 v19, 31, v18
	v_readlane_b32 s0, v243, 48
	v_lshlrev_b64 v[20:21], 11, v[18:19]
	v_readlane_b32 s1, v243, 49
	s_nop 1
	v_lshl_add_u64 v[20:21], s[0:1], 0, v[20:21]
	v_lshl_add_u64 v[20:21], v[142:143], 1, v[20:21]
	s_waitcnt vmcnt(22)
	v_lshlrev_b32_e32 v26, 16, v232
	v_and_b32_e32 v22, 0xffff0000, v232
	v_add_f32_e32 v15, v15, v22
	v_lshlrev_b32_e32 v22, 16, v233
	v_add_f32_e32 v16, v16, v22
	v_and_b32_e32 v22, 0xffff0000, v233
	v_add_f32_e32 v17, v17, v22
	v_lshlrev_b32_e32 v22, 16, v234
	v_add_f32_e32 v22, v10, v22
	v_and_b32_e32 v10, 0xffff0000, v234
	v_add_f32_e32 v23, v11, v10
	v_lshlrev_b32_e32 v10, 16, v235
	v_add_f32_e32 v24, v12, v10
	v_and_b32_e32 v10, 0xffff0000, v235
	v_add_f32_e32 v14, v14, v26
	v_add_f32_e32 v13, v13, v10
	v_cvt_pk_bf16_f32 v10, v14, v15
	v_cvt_pk_bf16_f32 v11, v16, v17
	v_cvt_pk_bf16_f32 v12, v22, v23
	v_cvt_pk_bf16_f32 v13, v24, v13
	global_store_dwordx4 v[20:21], v[10:13], off
	v_lshlrev_b32_e32 v14, 16, v10
	v_lshlrev_b32_e32 v15, 16, v11
	v_and_b32_e32 v10, 0xffff0000, v10
	v_mul_f32_e32 v22, v10, v10
	v_fmac_f32_e32 v22, v14, v14
	v_and_b32_e32 v11, 0xffff0000, v11
	v_fmac_f32_e32 v22, v15, v15
	v_lshlrev_b32_e32 v16, 16, v12
	v_fmac_f32_e32 v22, v11, v11
	v_and_b32_e32 v12, 0xffff0000, v12
	v_fmac_f32_e32 v22, v16, v16
	v_lshlrev_b32_e32 v17, 16, v13
	v_fmac_f32_e32 v22, v12, v12
	v_and_b32_e32 v13, 0xffff0000, v13
	v_fmac_f32_e32 v22, v17, v17
	v_fmac_f32_e32 v22, v13, v13
	s_waitcnt vmcnt(22)
	v_lshlrev_b32_e32 v14, 16, v236
	v_and_b32_e32 v10, 0xffff0000, v236
	v_add_f32_e32 v7, v7, v10
	v_lshlrev_b32_e32 v10, 16, v237
	v_add_f32_e32 v8, v8, v10
	v_and_b32_e32 v10, 0xffff0000, v237
	v_add_f32_e32 v9, v9, v10
	v_lshlrev_b32_e32 v10, 16, v238
	v_add_f32_e32 v10, v2, v10
	v_and_b32_e32 v2, 0xffff0000, v238
	v_add_f32_e32 v11, v3, v2
	v_lshlrev_b32_e32 v2, 16, v239
	v_add_f32_e32 v12, v4, v2
	v_and_b32_e32 v2, 0xffff0000, v239
	v_add_f32_e32 v6, v6, v14
	v_add_f32_e32 v5, v5, v2
	v_cvt_pk_bf16_f32 v2, v6, v7
	v_cvt_pk_bf16_f32 v3, v8, v9
	v_cvt_pk_bf16_f32 v4, v10, v11
	v_cvt_pk_bf16_f32 v5, v12, v5
	global_store_dwordx4 v[20:21], v[2:5], off offset:256
	v_lshlrev_b32_e32 v6, 16, v2
	v_lshlrev_b32_e32 v7, 16, v3
	v_and_b32_e32 v2, 0xffff0000, v2
	v_mul_f32_e32 v2, v2, v2
	v_fmac_f32_e32 v2, v6, v6
	v_and_b32_e32 v3, 0xffff0000, v3
	v_fmac_f32_e32 v2, v7, v7
	v_lshlrev_b32_e32 v8, 16, v4
	v_fmac_f32_e32 v2, v3, v3
	v_and_b32_e32 v4, 0xffff0000, v4
	v_fmac_f32_e32 v2, v8, v8
	v_lshlrev_b32_e32 v9, 16, v5
	v_fmac_f32_e32 v2, v4, v4
	v_and_b32_e32 v5, 0xffff0000, v5
	v_fmac_f32_e32 v2, v9, v9
	v_fmac_f32_e32 v2, v5, v5
	v_add_f32_e32 v2, v22, v2
	ds_bpermute_b32 v3, v152, v2
	s_waitcnt lgkmcnt(0)
	v_add_f32_e32 v2, v2, v3
	ds_bpermute_b32 v3, v151, v2
	s_and_saveexec_b64 s[0:1], vcc
	s_cbranch_execz .LBB0_686
	v_readlane_b32 s4, v242, 3
	s_waitcnt lgkmcnt(0)
	v_add_f32_e32 v4, v2, v3
	v_lshlrev_b64 v[2:3], 6, v[18:19]
	v_readlane_b32 s5, v242, 4
	s_lshl_b32 s92, s26, 2
	s_nop 0
	v_lshl_add_u64 v[2:3], s[4:5], 0, v[2:3]
	v_lshl_add_u64 v[2:3], s[18:19], 2, v[2:3]
	v_lshl_add_u64 v[2:3], v[2:3], 0, s[92:93]
	global_store_dword v[2:3], v4, off
	s_branch .LBB0_686
